# ffn_up epilogue: straight-line fast path (no boundary selects, streamed LDS rows, 2 rows interleaved) for waves without sequence boundaries
# speedup vs baseline: 1.0814x; 1.0072x over previous
.LBB0_1077:
	s_or_b64 exec, exec, s[4:5]
	v_lshl_or_b32 v132, s30, 7, v162
	v_ashrrev_i32_e32 v133, 31, v132
	s_sub_i32 s2, 0x4201, s31
	v_lshlrev_b64 v[128:129], 2, v[132:133]
	v_min_i32_e32 v170, s2, v164
	v_add_u32_e32 v180, s31, v165
	v_lshl_add_u64 v[136:137], s[16:17], 0, v[128:129]
	v_lshl_add_u64 v[134:135], s[0:1], 0, v[128:129]
	v_cmp_lt_i32_e64 s[2:3], v163, v170
	v_mul_hi_i32 v181, v180, s35
	s_waitcnt lgkmcnt(0)
	s_barrier
	s_and_saveexec_b64 s[30:31], s[2:3]
	s_cbranch_execz .LBB0_1080
	v_lshl_add_u64 v[130:131], s[6:7], 0, v[128:129]
	v_lshl_add_u64 v[144:145], s[18:19], 0, v[128:129]
	v_lshl_add_u64 v[146:147], s[20:21], 0, v[128:129]
	v_lshl_add_u64 v[148:149], s[22:23], 0, v[128:129]
	global_load_dwordx2 v[138:139], v[136:137], off
	global_load_dwordx2 v[140:141], v[134:135], off
	global_load_dwordx2 v[142:143], v[130:131], off
	s_nop 0
	global_load_dwordx2 v[144:145], v[144:145], off
	s_nop 0
	global_load_dwordx2 v[146:147], v[146:147], off
	s_nop 0
	global_load_dwordx2 v[148:149], v[148:149], off
	v_lshl_add_u64 v[130:131], s[24:25], 0, v[128:129]
	v_lshl_add_u64 v[128:129], s[26:27], 0, v[128:129]
	global_load_dwordx2 v[150:151], v[130:131], off
	global_load_dwordx2 v[152:153], v[128:129], off
	v_mov_b64_e32 v[128:129], s[14:15]
	v_mad_i64_i32 v[128:129], s[4:5], v180, s87, v[128:129]
	v_lshl_add_u64 v[154:155], v[132:133], 1, v[128:129]
	v_lshrrev_b32_e32 v128, 31, v181
	v_ashrrev_i32_e32 v129, 11, v181
	v_add_u32_e32 v128, v129, v128
	v_mul_i32_i24_e32 v128, 0x2100, v128
	v_sub_u32_e32 v182, v180, v128
	ds_read2_b64 v[128:131], v166 offset1:16
	ds_read_b64 v[160:161], v167
	ds_read_b64 v[158:159], v168
	s_mov_b64 s[40:41], 0
	v_mov_b32_e32 v183, v169
	v_mov_b32_e32 v184, v163
	s_waitcnt lgkmcnt(2)
	v_mov_b64_e32 v[156:157], v[128:129]
	s_waitcnt vmcnt(0)
	v_add_u32_e32 v236, 0xfffffeff, v182
	s_movk_i32 s40, 0x1fef
	v_cmp_le_u32_e64 s[4:5], s40, v236
	v_sub_u32_e32 v236, v170, v184
	v_cmp_gt_u32_e64 s[40:41], 15, v236
	s_or_b64 s[4:5], s[4:5], s[40:41]
	s_cmp_lg_u64 s[4:5], 0
	s_cbranch_scc0 .Lffnepi0_fast
	s_mov_b64 s[40:41], 0
	s_branch .LBB0_1079
.Lffnepi0_fast:
	v_add_u32_e32 v236, 15, v184
	v_cmp_lt_i32_e64 s[4:5], v236, v170
	v_mov_b32_e32 v235, v183
	ds_read2_b64 v[192:195], v235 offset0:0 offset1:16
	ds_read2_b64 v[198:201], v235 offset0:64 offset1:80
	ds_read2_b64 v[204:207], v235 offset0:128 offset1:144
	ds_read2_b64 v[208:211], v235 offset0:192 offset1:208
	v_add_u32_e32 v235, 0x800, v235
	ds_read2_b64 v[212:215], v235 offset0:0 offset1:16
	s_waitcnt lgkmcnt(3)
	v_pk_fma_f32 v[128:129], v[142:143], v[156:157], v[140:141]
	v_pk_fma_f32 v[228:229], v[142:143], v[192:193], v[140:141]
	v_pk_fma_f32 v[224:225], v[148:149], v[130:131], v[152:153]
	v_pk_fma_f32 v[230:231], v[148:149], v[194:195], v[152:153]
	v_pk_fma_f32 v[128:129], v[138:139], v[158:159], v[128:129]
	v_pk_fma_f32 v[228:229], v[138:139], v[156:157], v[228:229]
	v_pk_fma_f32 v[224:225], v[146:147], v[160:161], v[224:225]
	v_pk_fma_f32 v[230:231], v[146:147], v[130:131], v[230:231]
	v_pk_fma_f32 v[128:129], v[144:145], v[192:193], v[128:129]
	v_pk_fma_f32 v[228:229], v[144:145], v[198:199], v[228:229]
	v_pk_fma_f32 v[224:225], v[150:151], v[194:195], v[224:225]
	v_pk_fma_f32 v[230:231], v[150:151], v[200:201], v[230:231]
	v_mul_f32_e32 v185, 0xbfb8aa3b, v128
	v_mul_f32_e32 v234, 0xbfb8aa3b, v228
	v_exp_f32_e32 v185, v185
	v_exp_f32_e32 v234, v234
	v_add_f32_e32 v185, 1.0, v185
	v_add_f32_e32 v234, 1.0, v234
	v_rcp_f32_e32 v226, v185
	v_rcp_f32_e32 v232, v234
	v_mul_f32_e32 v185, 0xbfb8aa3b, v129
	v_mul_f32_e32 v234, 0xbfb8aa3b, v229
	v_exp_f32_e32 v185, v185
	v_exp_f32_e32 v234, v234
	v_add_f32_e32 v185, 1.0, v185
	v_add_f32_e32 v234, 1.0, v234
	v_rcp_f32_e32 v227, v185
	v_rcp_f32_e32 v233, v234
	v_pk_mul_f32 v[128:129], v[128:129], v[226:227]
	v_pk_mul_f32 v[228:229], v[228:229], v[232:233]
	v_pk_mul_f32 v[128:129], v[224:225], v[128:129]
	v_pk_mul_f32 v[228:229], v[230:231], v[228:229]
	v_cvt_pk_bf16_f32 v128, v128, v129
	v_cvt_pk_bf16_f32 v228, v228, v229
	global_store_dword v[154:155], v128, off
	v_lshl_add_u64 v[154:155], v[154:155], 0, s[38:39]
	global_store_dword v[154:155], v228, off
	v_lshl_add_u64 v[154:155], v[154:155], 0, s[38:39]
	ds_read2_b64 v[216:219], v235 offset0:64 offset1:80
	ds_read2_b64 v[220:223], v235 offset0:128 offset1:144
	s_waitcnt lgkmcnt(3)
	v_pk_fma_f32 v[128:129], v[142:143], v[198:199], v[140:141]
	v_pk_fma_f32 v[228:229], v[142:143], v[204:205], v[140:141]
	v_pk_fma_f32 v[224:225], v[148:149], v[200:201], v[152:153]
	v_pk_fma_f32 v[230:231], v[148:149], v[206:207], v[152:153]
	v_pk_fma_f32 v[128:129], v[138:139], v[192:193], v[128:129]
	v_pk_fma_f32 v[228:229], v[138:139], v[198:199], v[228:229]
	v_pk_fma_f32 v[224:225], v[146:147], v[194:195], v[224:225]
	v_pk_fma_f32 v[230:231], v[146:147], v[200:201], v[230:231]
	v_pk_fma_f32 v[128:129], v[144:145], v[204:205], v[128:129]
	v_pk_fma_f32 v[228:229], v[144:145], v[208:209], v[228:229]
	v_pk_fma_f32 v[224:225], v[150:151], v[206:207], v[224:225]
	v_pk_fma_f32 v[230:231], v[150:151], v[210:211], v[230:231]
	v_mul_f32_e32 v185, 0xbfb8aa3b, v128
	v_mul_f32_e32 v234, 0xbfb8aa3b, v228
	v_exp_f32_e32 v185, v185
	v_exp_f32_e32 v234, v234
	v_add_f32_e32 v185, 1.0, v185
	v_add_f32_e32 v234, 1.0, v234
	v_rcp_f32_e32 v226, v185
	v_rcp_f32_e32 v232, v234
	v_mul_f32_e32 v185, 0xbfb8aa3b, v129
	v_mul_f32_e32 v234, 0xbfb8aa3b, v229
	v_exp_f32_e32 v185, v185
	v_exp_f32_e32 v234, v234
	v_add_f32_e32 v185, 1.0, v185
	v_add_f32_e32 v234, 1.0, v234
	v_rcp_f32_e32 v227, v185
	v_rcp_f32_e32 v233, v234
	v_pk_mul_f32 v[128:129], v[128:129], v[226:227]
	v_pk_mul_f32 v[228:229], v[228:229], v[232:233]
	v_pk_mul_f32 v[128:129], v[224:225], v[128:129]
	v_pk_mul_f32 v[228:229], v[230:231], v[228:229]
	v_cvt_pk_bf16_f32 v128, v128, v129
	v_cvt_pk_bf16_f32 v228, v228, v229
	global_store_dword v[154:155], v128, off
	v_lshl_add_u64 v[154:155], v[154:155], 0, s[38:39]
	global_store_dword v[154:155], v228, off
	v_lshl_add_u64 v[154:155], v[154:155], 0, s[38:39]
	ds_read2_b64 v[186:189], v235 offset0:192 offset1:208
	v_add_u32_e32 v235, 0x800, v235
	ds_read2_b64 v[192:195], v235 offset0:0 offset1:16
	s_waitcnt lgkmcnt(3)
	v_pk_fma_f32 v[128:129], v[142:143], v[208:209], v[140:141]
	v_pk_fma_f32 v[228:229], v[142:143], v[212:213], v[140:141]
	v_pk_fma_f32 v[224:225], v[148:149], v[210:211], v[152:153]
	v_pk_fma_f32 v[230:231], v[148:149], v[214:215], v[152:153]
	v_pk_fma_f32 v[128:129], v[138:139], v[204:205], v[128:129]
	v_pk_fma_f32 v[228:229], v[138:139], v[208:209], v[228:229]
	v_pk_fma_f32 v[224:225], v[146:147], v[206:207], v[224:225]
	v_pk_fma_f32 v[230:231], v[146:147], v[210:211], v[230:231]
	v_pk_fma_f32 v[128:129], v[144:145], v[212:213], v[128:129]
	v_pk_fma_f32 v[228:229], v[144:145], v[216:217], v[228:229]
	v_pk_fma_f32 v[224:225], v[150:151], v[214:215], v[224:225]
	v_pk_fma_f32 v[230:231], v[150:151], v[218:219], v[230:231]
	v_mul_f32_e32 v185, 0xbfb8aa3b, v128
	v_mul_f32_e32 v234, 0xbfb8aa3b, v228
	v_exp_f32_e32 v185, v185
	v_exp_f32_e32 v234, v234
	v_add_f32_e32 v185, 1.0, v185
	v_add_f32_e32 v234, 1.0, v234
	v_rcp_f32_e32 v226, v185
	v_rcp_f32_e32 v232, v234
	v_mul_f32_e32 v185, 0xbfb8aa3b, v129
	v_mul_f32_e32 v234, 0xbfb8aa3b, v229
	v_exp_f32_e32 v185, v185
	v_exp_f32_e32 v234, v234
	v_add_f32_e32 v185, 1.0, v185
	v_add_f32_e32 v234, 1.0, v234
	v_rcp_f32_e32 v227, v185
	v_rcp_f32_e32 v233, v234
	v_pk_mul_f32 v[128:129], v[128:129], v[226:227]
	v_pk_mul_f32 v[228:229], v[228:229], v[232:233]
	v_pk_mul_f32 v[128:129], v[224:225], v[128:129]
	v_pk_mul_f32 v[228:229], v[230:231], v[228:229]
	v_cvt_pk_bf16_f32 v128, v128, v129
	v_cvt_pk_bf16_f32 v228, v228, v229
	global_store_dword v[154:155], v128, off
	v_lshl_add_u64 v[154:155], v[154:155], 0, s[38:39]
	global_store_dword v[154:155], v228, off
	v_lshl_add_u64 v[154:155], v[154:155], 0, s[38:39]
	ds_read2_b64 v[198:201], v235 offset0:64 offset1:80
	ds_read2_b64 v[204:207], v235 offset0:128 offset1:144
	s_waitcnt lgkmcnt(3)
	v_pk_fma_f32 v[128:129], v[142:143], v[216:217], v[140:141]
	v_pk_fma_f32 v[228:229], v[142:143], v[220:221], v[140:141]
	v_pk_fma_f32 v[224:225], v[148:149], v[218:219], v[152:153]
	v_pk_fma_f32 v[230:231], v[148:149], v[222:223], v[152:153]
	v_pk_fma_f32 v[128:129], v[138:139], v[212:213], v[128:129]
	v_pk_fma_f32 v[228:229], v[138:139], v[216:217], v[228:229]
	v_pk_fma_f32 v[224:225], v[146:147], v[214:215], v[224:225]
	v_pk_fma_f32 v[230:231], v[146:147], v[218:219], v[230:231]
	v_pk_fma_f32 v[128:129], v[144:145], v[220:221], v[128:129]
	v_pk_fma_f32 v[228:229], v[144:145], v[186:187], v[228:229]
	v_pk_fma_f32 v[224:225], v[150:151], v[222:223], v[224:225]
	v_pk_fma_f32 v[230:231], v[150:151], v[188:189], v[230:231]
	v_mul_f32_e32 v185, 0xbfb8aa3b, v128
	v_mul_f32_e32 v234, 0xbfb8aa3b, v228
	v_exp_f32_e32 v185, v185
	v_exp_f32_e32 v234, v234
	v_add_f32_e32 v185, 1.0, v185
	v_add_f32_e32 v234, 1.0, v234
	v_rcp_f32_e32 v226, v185
	v_rcp_f32_e32 v232, v234
	v_mul_f32_e32 v185, 0xbfb8aa3b, v129
	v_mul_f32_e32 v234, 0xbfb8aa3b, v229
	v_exp_f32_e32 v185, v185
	v_exp_f32_e32 v234, v234
	v_add_f32_e32 v185, 1.0, v185
	v_add_f32_e32 v234, 1.0, v234
	v_rcp_f32_e32 v227, v185
	v_rcp_f32_e32 v233, v234
	v_pk_mul_f32 v[128:129], v[128:129], v[226:227]
	v_pk_mul_f32 v[228:229], v[228:229], v[232:233]
	v_pk_mul_f32 v[128:129], v[224:225], v[128:129]
	v_pk_mul_f32 v[228:229], v[230:231], v[228:229]
	v_cvt_pk_bf16_f32 v128, v128, v129
	v_cvt_pk_bf16_f32 v228, v228, v229
	global_store_dword v[154:155], v128, off
	v_lshl_add_u64 v[154:155], v[154:155], 0, s[38:39]
	global_store_dword v[154:155], v228, off
	v_lshl_add_u64 v[154:155], v[154:155], 0, s[38:39]
	ds_read2_b64 v[208:211], v235 offset0:192 offset1:208
	v_add_u32_e32 v235, 0x800, v235
	ds_read2_b64 v[212:215], v235 offset0:0 offset1:16
	s_waitcnt lgkmcnt(3)
	v_pk_fma_f32 v[128:129], v[142:143], v[186:187], v[140:141]
	v_pk_fma_f32 v[228:229], v[142:143], v[192:193], v[140:141]
	v_pk_fma_f32 v[224:225], v[148:149], v[188:189], v[152:153]
	v_pk_fma_f32 v[230:231], v[148:149], v[194:195], v[152:153]
	v_pk_fma_f32 v[128:129], v[138:139], v[220:221], v[128:129]
	v_pk_fma_f32 v[228:229], v[138:139], v[186:187], v[228:229]
	v_pk_fma_f32 v[224:225], v[146:147], v[222:223], v[224:225]
	v_pk_fma_f32 v[230:231], v[146:147], v[188:189], v[230:231]
	v_pk_fma_f32 v[128:129], v[144:145], v[192:193], v[128:129]
	v_pk_fma_f32 v[228:229], v[144:145], v[198:199], v[228:229]
	v_pk_fma_f32 v[224:225], v[150:151], v[194:195], v[224:225]
	v_pk_fma_f32 v[230:231], v[150:151], v[200:201], v[230:231]
	v_mul_f32_e32 v185, 0xbfb8aa3b, v128
	v_mul_f32_e32 v234, 0xbfb8aa3b, v228
	v_exp_f32_e32 v185, v185
	v_exp_f32_e32 v234, v234
	v_add_f32_e32 v185, 1.0, v185
	v_add_f32_e32 v234, 1.0, v234
	v_rcp_f32_e32 v226, v185
	v_rcp_f32_e32 v232, v234
	v_mul_f32_e32 v185, 0xbfb8aa3b, v129
	v_mul_f32_e32 v234, 0xbfb8aa3b, v229
	v_exp_f32_e32 v185, v185
	v_exp_f32_e32 v234, v234
	v_add_f32_e32 v185, 1.0, v185
	v_add_f32_e32 v234, 1.0, v234
	v_rcp_f32_e32 v227, v185
	v_rcp_f32_e32 v233, v234
	v_pk_mul_f32 v[128:129], v[128:129], v[226:227]
	v_pk_mul_f32 v[228:229], v[228:229], v[232:233]
	v_pk_mul_f32 v[128:129], v[224:225], v[128:129]
	v_pk_mul_f32 v[228:229], v[230:231], v[228:229]
	v_cvt_pk_bf16_f32 v128, v128, v129
	v_cvt_pk_bf16_f32 v228, v228, v229
	global_store_dword v[154:155], v128, off
	v_lshl_add_u64 v[154:155], v[154:155], 0, s[38:39]
	global_store_dword v[154:155], v228, off
	v_lshl_add_u64 v[154:155], v[154:155], 0, s[38:39]
	ds_read2_b64 v[216:219], v235 offset0:64 offset1:80
	ds_read2_b64 v[220:223], v235 offset0:128 offset1:144
	s_waitcnt lgkmcnt(3)
	v_pk_fma_f32 v[128:129], v[142:143], v[198:199], v[140:141]
	v_pk_fma_f32 v[228:229], v[142:143], v[204:205], v[140:141]
	v_pk_fma_f32 v[224:225], v[148:149], v[200:201], v[152:153]
	v_pk_fma_f32 v[230:231], v[148:149], v[206:207], v[152:153]
	v_pk_fma_f32 v[128:129], v[138:139], v[192:193], v[128:129]
	v_pk_fma_f32 v[228:229], v[138:139], v[198:199], v[228:229]
	v_pk_fma_f32 v[224:225], v[146:147], v[194:195], v[224:225]
	v_pk_fma_f32 v[230:231], v[146:147], v[200:201], v[230:231]
	v_pk_fma_f32 v[128:129], v[144:145], v[204:205], v[128:129]
	v_pk_fma_f32 v[228:229], v[144:145], v[208:209], v[228:229]
	v_pk_fma_f32 v[224:225], v[150:151], v[206:207], v[224:225]
	v_pk_fma_f32 v[230:231], v[150:151], v[210:211], v[230:231]
	v_mul_f32_e32 v185, 0xbfb8aa3b, v128
	v_mul_f32_e32 v234, 0xbfb8aa3b, v228
	v_exp_f32_e32 v185, v185
	v_exp_f32_e32 v234, v234
	v_add_f32_e32 v185, 1.0, v185
	v_add_f32_e32 v234, 1.0, v234
	v_rcp_f32_e32 v226, v185
	v_rcp_f32_e32 v232, v234
	v_mul_f32_e32 v185, 0xbfb8aa3b, v129
	v_mul_f32_e32 v234, 0xbfb8aa3b, v229
	v_exp_f32_e32 v185, v185
	v_exp_f32_e32 v234, v234
	v_add_f32_e32 v185, 1.0, v185
	v_add_f32_e32 v234, 1.0, v234
	v_rcp_f32_e32 v227, v185
	v_rcp_f32_e32 v233, v234
	v_pk_mul_f32 v[128:129], v[128:129], v[226:227]
	v_pk_mul_f32 v[228:229], v[228:229], v[232:233]
	v_pk_mul_f32 v[128:129], v[224:225], v[128:129]
	v_pk_mul_f32 v[228:229], v[230:231], v[228:229]
	v_cvt_pk_bf16_f32 v128, v128, v129
	v_cvt_pk_bf16_f32 v228, v228, v229
	global_store_dword v[154:155], v128, off
	v_lshl_add_u64 v[154:155], v[154:155], 0, s[38:39]
	global_store_dword v[154:155], v228, off
	v_lshl_add_u64 v[154:155], v[154:155], 0, s[38:39]
	ds_read2_b64 v[186:189], v235 offset0:192 offset1:208
	s_waitcnt lgkmcnt(2)
	v_pk_fma_f32 v[128:129], v[142:143], v[208:209], v[140:141]
	v_pk_fma_f32 v[228:229], v[142:143], v[212:213], v[140:141]
	v_pk_fma_f32 v[224:225], v[148:149], v[210:211], v[152:153]
	v_pk_fma_f32 v[230:231], v[148:149], v[214:215], v[152:153]
	v_pk_fma_f32 v[128:129], v[138:139], v[204:205], v[128:129]
	v_pk_fma_f32 v[228:229], v[138:139], v[208:209], v[228:229]
	v_pk_fma_f32 v[224:225], v[146:147], v[206:207], v[224:225]
	v_pk_fma_f32 v[230:231], v[146:147], v[210:211], v[230:231]
	v_pk_fma_f32 v[128:129], v[144:145], v[212:213], v[128:129]
	v_pk_fma_f32 v[228:229], v[144:145], v[216:217], v[228:229]
	v_pk_fma_f32 v[224:225], v[150:151], v[214:215], v[224:225]
	v_pk_fma_f32 v[230:231], v[150:151], v[218:219], v[230:231]
	v_mul_f32_e32 v185, 0xbfb8aa3b, v128
	v_mul_f32_e32 v234, 0xbfb8aa3b, v228
	v_exp_f32_e32 v185, v185
	v_exp_f32_e32 v234, v234
	v_add_f32_e32 v185, 1.0, v185
	v_add_f32_e32 v234, 1.0, v234
	v_rcp_f32_e32 v226, v185
	v_rcp_f32_e32 v232, v234
	v_mul_f32_e32 v185, 0xbfb8aa3b, v129
	v_mul_f32_e32 v234, 0xbfb8aa3b, v229
	v_exp_f32_e32 v185, v185
	v_exp_f32_e32 v234, v234
	v_add_f32_e32 v185, 1.0, v185
	v_add_f32_e32 v234, 1.0, v234
	v_rcp_f32_e32 v227, v185
	v_rcp_f32_e32 v233, v234
	v_pk_mul_f32 v[128:129], v[128:129], v[226:227]
	v_pk_mul_f32 v[228:229], v[228:229], v[232:233]
	v_pk_mul_f32 v[128:129], v[224:225], v[128:129]
	v_pk_mul_f32 v[228:229], v[230:231], v[228:229]
	v_cvt_pk_bf16_f32 v128, v128, v129
	v_cvt_pk_bf16_f32 v228, v228, v229
	global_store_dword v[154:155], v128, off
	v_lshl_add_u64 v[154:155], v[154:155], 0, s[38:39]
	global_store_dword v[154:155], v228, off
	v_lshl_add_u64 v[154:155], v[154:155], 0, s[38:39]
	s_waitcnt lgkmcnt(0)
	v_pk_fma_f32 v[128:129], v[142:143], v[216:217], v[140:141]
	v_pk_fma_f32 v[228:229], v[142:143], v[220:221], v[140:141]
	v_pk_fma_f32 v[224:225], v[148:149], v[218:219], v[152:153]
	v_pk_fma_f32 v[230:231], v[148:149], v[222:223], v[152:153]
	v_pk_fma_f32 v[128:129], v[138:139], v[212:213], v[128:129]
	v_pk_fma_f32 v[228:229], v[138:139], v[216:217], v[228:229]
	v_pk_fma_f32 v[224:225], v[146:147], v[214:215], v[224:225]
	v_pk_fma_f32 v[230:231], v[146:147], v[218:219], v[230:231]
	v_pk_fma_f32 v[128:129], v[144:145], v[220:221], v[128:129]
	v_pk_fma_f32 v[228:229], v[144:145], v[186:187], v[228:229]
	v_pk_fma_f32 v[224:225], v[150:151], v[222:223], v[224:225]
	v_pk_fma_f32 v[230:231], v[150:151], v[188:189], v[230:231]
	v_mul_f32_e32 v185, 0xbfb8aa3b, v128
	v_mul_f32_e32 v234, 0xbfb8aa3b, v228
	v_exp_f32_e32 v185, v185
	v_exp_f32_e32 v234, v234
	v_add_f32_e32 v185, 1.0, v185
	v_add_f32_e32 v234, 1.0, v234
	v_rcp_f32_e32 v226, v185
	v_rcp_f32_e32 v232, v234
	v_mul_f32_e32 v185, 0xbfb8aa3b, v129
	v_mul_f32_e32 v234, 0xbfb8aa3b, v229
	v_exp_f32_e32 v185, v185
	v_exp_f32_e32 v234, v234
	v_add_f32_e32 v185, 1.0, v185
	v_add_f32_e32 v234, 1.0, v234
	v_rcp_f32_e32 v227, v185
	v_rcp_f32_e32 v233, v234
	v_pk_mul_f32 v[128:129], v[128:129], v[226:227]
	v_pk_mul_f32 v[228:229], v[228:229], v[232:233]
	v_pk_mul_f32 v[128:129], v[224:225], v[128:129]
	v_pk_mul_f32 v[228:229], v[230:231], v[228:229]
	v_cvt_pk_bf16_f32 v128, v128, v129
	v_cvt_pk_bf16_f32 v228, v228, v229
	global_store_dword v[154:155], v128, off
	v_lshl_add_u64 v[154:155], v[154:155], 0, s[38:39]
	s_and_saveexec_b64 s[40:41], s[4:5]
	global_store_dword v[154:155], v228, off
	s_or_b64 exec, exec, s[40:41]
	s_branch .LBB0_1080

.LBB0_1082:
	s_or_b64 exec, exec, s[4:5]
	s_waitcnt lgkmcnt(0)
	s_barrier
	s_and_saveexec_b64 s[4:5], s[2:3]
	s_cbranch_execz .LBB0_1066
	v_or_b32_e32 v0, 64, v132
	v_ashrrev_i32_e32 v1, 31, v0
	v_lshlrev_b64 v[0:1], 2, v[0:1]
	v_lshl_add_u64 v[2:3], s[6:7], 0, v[0:1]
	v_lshl_add_u64 v[10:11], s[18:19], 0, v[0:1]
	v_lshl_add_u64 v[12:13], s[20:21], 0, v[0:1]
	v_lshl_add_u64 v[14:15], s[22:23], 0, v[0:1]
	global_load_dwordx2 v[4:5], v[136:137], off offset:256
	global_load_dwordx2 v[6:7], v[134:135], off offset:256
	global_load_dwordx2 v[8:9], v[2:3], off
	s_nop 0
	global_load_dwordx2 v[10:11], v[10:11], off
	s_nop 0
	global_load_dwordx2 v[12:13], v[12:13], off
	s_nop 0
	global_load_dwordx2 v[14:15], v[14:15], off
	v_lshl_add_u64 v[2:3], s[24:25], 0, v[0:1]
	v_lshl_add_u64 v[0:1], s[26:27], 0, v[0:1]
	global_load_dwordx2 v[16:17], v[2:3], off
	global_load_dwordx2 v[18:19], v[0:1], off
	v_mov_b64_e32 v[0:1], s[14:15]
	v_mad_i64_i32 v[0:1], s[2:3], v180, s87, v[0:1]
	v_lshl_add_u64 v[0:1], v[132:133], 1, v[0:1]
	v_lshl_add_u64 v[20:21], v[0:1], 0, s[66:67]
	v_lshrrev_b32_e32 v0, 31, v181
	v_ashrrev_i32_e32 v1, 11, v181
	v_add_u32_e32 v0, v1, v0
	v_mul_i32_i24_e32 v0, 0x2100, v0
	v_sub_u32_e32 v28, v180, v0
	ds_read2_b64 v[0:3], v166 offset1:16
	ds_read_b64 v[26:27], v167
	ds_read_b64 v[24:25], v168
	s_mov_b64 s[2:3], 0
	v_mov_b32_e32 v29, v169
	v_mov_b32_e32 v30, v163
	s_waitcnt lgkmcnt(2)
	v_mov_b64_e32 v[22:23], v[0:1]
	s_waitcnt vmcnt(0)
	v_add_u32_e32 v118, 0xfffffeff, v28
	v_cmp_le_u32_e32 vcc, 0x1fef, v118
	v_sub_u32_e32 v118, v170, v30
	v_cmp_gt_u32_e64 s[2:3], 15, v118
	s_or_b64 vcc, vcc, s[2:3]
	s_cmp_lg_u64 vcc, 0
	s_cbranch_scc0 .Lffnepi1_fast
	s_mov_b64 s[2:3], 0
	s_branch .LBB0_1084
.Lffnepi1_fast:
	v_add_u32_e32 v118, 15, v30
	v_cmp_lt_i32_e32 vcc, v118, v170
	v_mov_b32_e32 v117, v29
	ds_read2_b64 v[56:59], v117 offset0:0 offset1:16
	ds_read2_b64 v[60:63], v117 offset0:64 offset1:80
	ds_read2_b64 v[64:67], v117 offset0:128 offset1:144
	ds_read2_b64 v[68:71], v117 offset0:192 offset1:208
	v_add_u32_e32 v117, 0x800, v117
	ds_read2_b64 v[72:75], v117 offset0:0 offset1:16
	s_waitcnt lgkmcnt(3)
	v_pk_fma_f32 v[36:37], v[8:9], v[22:23], v[6:7]
	v_pk_fma_f32 v[110:111], v[8:9], v[56:57], v[6:7]
	v_pk_fma_f32 v[106:107], v[14:15], v[2:3], v[18:19]
	v_pk_fma_f32 v[112:113], v[14:15], v[58:59], v[18:19]
	v_pk_fma_f32 v[36:37], v[4:5], v[24:25], v[36:37]
	v_pk_fma_f32 v[110:111], v[4:5], v[22:23], v[110:111]
	v_pk_fma_f32 v[106:107], v[12:13], v[26:27], v[106:107]
	v_pk_fma_f32 v[112:113], v[12:13], v[2:3], v[112:113]
	v_pk_fma_f32 v[36:37], v[10:11], v[56:57], v[36:37]
	v_pk_fma_f32 v[110:111], v[10:11], v[60:61], v[110:111]
	v_pk_fma_f32 v[106:107], v[16:17], v[58:59], v[106:107]
	v_pk_fma_f32 v[112:113], v[16:17], v[62:63], v[112:113]
	v_mul_f32_e32 v31, 0xbfb8aa3b, v36
	v_mul_f32_e32 v116, 0xbfb8aa3b, v110
	v_exp_f32_e32 v31, v31
	v_exp_f32_e32 v116, v116
	v_add_f32_e32 v31, 1.0, v31
	v_add_f32_e32 v116, 1.0, v116
	v_rcp_f32_e32 v108, v31
	v_rcp_f32_e32 v114, v116
	v_mul_f32_e32 v31, 0xbfb8aa3b, v37
	v_mul_f32_e32 v116, 0xbfb8aa3b, v111
	v_exp_f32_e32 v31, v31
	v_exp_f32_e32 v116, v116
	v_add_f32_e32 v31, 1.0, v31
	v_add_f32_e32 v116, 1.0, v116
	v_rcp_f32_e32 v109, v31
	v_rcp_f32_e32 v115, v116
	v_pk_mul_f32 v[36:37], v[36:37], v[108:109]
	v_pk_mul_f32 v[110:111], v[110:111], v[114:115]
	v_pk_mul_f32 v[36:37], v[106:107], v[36:37]
	v_pk_mul_f32 v[110:111], v[112:113], v[110:111]
	v_cvt_pk_bf16_f32 v36, v36, v37
	v_cvt_pk_bf16_f32 v110, v110, v111
	global_store_dword v[20:21], v36, off
	v_lshl_add_u64 v[20:21], v[20:21], 0, s[38:39]
	global_store_dword v[20:21], v110, off
	v_lshl_add_u64 v[20:21], v[20:21], 0, s[38:39]
	ds_read2_b64 v[76:79], v117 offset0:64 offset1:80
	ds_read2_b64 v[102:105], v117 offset0:128 offset1:144
	s_waitcnt lgkmcnt(3)
	v_pk_fma_f32 v[36:37], v[8:9], v[60:61], v[6:7]
	v_pk_fma_f32 v[110:111], v[8:9], v[64:65], v[6:7]
	v_pk_fma_f32 v[106:107], v[14:15], v[62:63], v[18:19]
	v_pk_fma_f32 v[112:113], v[14:15], v[66:67], v[18:19]
	v_pk_fma_f32 v[36:37], v[4:5], v[56:57], v[36:37]
	v_pk_fma_f32 v[110:111], v[4:5], v[60:61], v[110:111]
	v_pk_fma_f32 v[106:107], v[12:13], v[58:59], v[106:107]
	v_pk_fma_f32 v[112:113], v[12:13], v[62:63], v[112:113]
	v_pk_fma_f32 v[36:37], v[10:11], v[64:65], v[36:37]
	v_pk_fma_f32 v[110:111], v[10:11], v[68:69], v[110:111]
	v_pk_fma_f32 v[106:107], v[16:17], v[66:67], v[106:107]
	v_pk_fma_f32 v[112:113], v[16:17], v[70:71], v[112:113]
	v_mul_f32_e32 v31, 0xbfb8aa3b, v36
	v_mul_f32_e32 v116, 0xbfb8aa3b, v110
	v_exp_f32_e32 v31, v31
	v_exp_f32_e32 v116, v116
	v_add_f32_e32 v31, 1.0, v31
	v_add_f32_e32 v116, 1.0, v116
	v_rcp_f32_e32 v108, v31
	v_rcp_f32_e32 v114, v116
	v_mul_f32_e32 v31, 0xbfb8aa3b, v37
	v_mul_f32_e32 v116, 0xbfb8aa3b, v111
	v_exp_f32_e32 v31, v31
	v_exp_f32_e32 v116, v116
	v_add_f32_e32 v31, 1.0, v31
	v_add_f32_e32 v116, 1.0, v116
	v_rcp_f32_e32 v109, v31
	v_rcp_f32_e32 v115, v116
	v_pk_mul_f32 v[36:37], v[36:37], v[108:109]
	v_pk_mul_f32 v[110:111], v[110:111], v[114:115]
	v_pk_mul_f32 v[36:37], v[106:107], v[36:37]
	v_pk_mul_f32 v[110:111], v[112:113], v[110:111]
	v_cvt_pk_bf16_f32 v36, v36, v37
	v_cvt_pk_bf16_f32 v110, v110, v111
	global_store_dword v[20:21], v36, off
	v_lshl_add_u64 v[20:21], v[20:21], 0, s[38:39]
	global_store_dword v[20:21], v110, off
	v_lshl_add_u64 v[20:21], v[20:21], 0, s[38:39]
	ds_read2_b64 v[32:35], v117 offset0:192 offset1:208
	v_add_u32_e32 v117, 0x800, v117
	ds_read2_b64 v[56:59], v117 offset0:0 offset1:16
	s_waitcnt lgkmcnt(3)
	v_pk_fma_f32 v[36:37], v[8:9], v[68:69], v[6:7]
	v_pk_fma_f32 v[110:111], v[8:9], v[72:73], v[6:7]
	v_pk_fma_f32 v[106:107], v[14:15], v[70:71], v[18:19]
	v_pk_fma_f32 v[112:113], v[14:15], v[74:75], v[18:19]
	v_pk_fma_f32 v[36:37], v[4:5], v[64:65], v[36:37]
	v_pk_fma_f32 v[110:111], v[4:5], v[68:69], v[110:111]
	v_pk_fma_f32 v[106:107], v[12:13], v[66:67], v[106:107]
	v_pk_fma_f32 v[112:113], v[12:13], v[70:71], v[112:113]
	v_pk_fma_f32 v[36:37], v[10:11], v[72:73], v[36:37]
	v_pk_fma_f32 v[110:111], v[10:11], v[76:77], v[110:111]
	v_pk_fma_f32 v[106:107], v[16:17], v[74:75], v[106:107]
	v_pk_fma_f32 v[112:113], v[16:17], v[78:79], v[112:113]
	v_mul_f32_e32 v31, 0xbfb8aa3b, v36
	v_mul_f32_e32 v116, 0xbfb8aa3b, v110
	v_exp_f32_e32 v31, v31
	v_exp_f32_e32 v116, v116
	v_add_f32_e32 v31, 1.0, v31
	v_add_f32_e32 v116, 1.0, v116
	v_rcp_f32_e32 v108, v31
	v_rcp_f32_e32 v114, v116
	v_mul_f32_e32 v31, 0xbfb8aa3b, v37
	v_mul_f32_e32 v116, 0xbfb8aa3b, v111
	v_exp_f32_e32 v31, v31
	v_exp_f32_e32 v116, v116
	v_add_f32_e32 v31, 1.0, v31
	v_add_f32_e32 v116, 1.0, v116
	v_rcp_f32_e32 v109, v31
	v_rcp_f32_e32 v115, v116
	v_pk_mul_f32 v[36:37], v[36:37], v[108:109]
	v_pk_mul_f32 v[110:111], v[110:111], v[114:115]
	v_pk_mul_f32 v[36:37], v[106:107], v[36:37]
	v_pk_mul_f32 v[110:111], v[112:113], v[110:111]
	v_cvt_pk_bf16_f32 v36, v36, v37
	v_cvt_pk_bf16_f32 v110, v110, v111
	global_store_dword v[20:21], v36, off
	v_lshl_add_u64 v[20:21], v[20:21], 0, s[38:39]
	global_store_dword v[20:21], v110, off
	v_lshl_add_u64 v[20:21], v[20:21], 0, s[38:39]
	ds_read2_b64 v[60:63], v117 offset0:64 offset1:80
	ds_read2_b64 v[64:67], v117 offset0:128 offset1:144
	s_waitcnt lgkmcnt(3)
	v_pk_fma_f32 v[36:37], v[8:9], v[76:77], v[6:7]
	v_pk_fma_f32 v[110:111], v[8:9], v[102:103], v[6:7]
	v_pk_fma_f32 v[106:107], v[14:15], v[78:79], v[18:19]
	v_pk_fma_f32 v[112:113], v[14:15], v[104:105], v[18:19]
	v_pk_fma_f32 v[36:37], v[4:5], v[72:73], v[36:37]
	v_pk_fma_f32 v[110:111], v[4:5], v[76:77], v[110:111]
	v_pk_fma_f32 v[106:107], v[12:13], v[74:75], v[106:107]
	v_pk_fma_f32 v[112:113], v[12:13], v[78:79], v[112:113]
	v_pk_fma_f32 v[36:37], v[10:11], v[102:103], v[36:37]
	v_pk_fma_f32 v[110:111], v[10:11], v[32:33], v[110:111]
	v_pk_fma_f32 v[106:107], v[16:17], v[104:105], v[106:107]
	v_pk_fma_f32 v[112:113], v[16:17], v[34:35], v[112:113]
	v_mul_f32_e32 v31, 0xbfb8aa3b, v36
	v_mul_f32_e32 v116, 0xbfb8aa3b, v110
	v_exp_f32_e32 v31, v31
	v_exp_f32_e32 v116, v116
	v_add_f32_e32 v31, 1.0, v31
	v_add_f32_e32 v116, 1.0, v116
	v_rcp_f32_e32 v108, v31
	v_rcp_f32_e32 v114, v116
	v_mul_f32_e32 v31, 0xbfb8aa3b, v37
	v_mul_f32_e32 v116, 0xbfb8aa3b, v111
	v_exp_f32_e32 v31, v31
	v_exp_f32_e32 v116, v116
	v_add_f32_e32 v31, 1.0, v31
	v_add_f32_e32 v116, 1.0, v116
	v_rcp_f32_e32 v109, v31
	v_rcp_f32_e32 v115, v116
	v_pk_mul_f32 v[36:37], v[36:37], v[108:109]
	v_pk_mul_f32 v[110:111], v[110:111], v[114:115]
	v_pk_mul_f32 v[36:37], v[106:107], v[36:37]
	v_pk_mul_f32 v[110:111], v[112:113], v[110:111]
	v_cvt_pk_bf16_f32 v36, v36, v37
	v_cvt_pk_bf16_f32 v110, v110, v111
	global_store_dword v[20:21], v36, off
	v_lshl_add_u64 v[20:21], v[20:21], 0, s[38:39]
	global_store_dword v[20:21], v110, off
	v_lshl_add_u64 v[20:21], v[20:21], 0, s[38:39]
	ds_read2_b64 v[68:71], v117 offset0:192 offset1:208
	v_add_u32_e32 v117, 0x800, v117
	ds_read2_b64 v[72:75], v117 offset0:0 offset1:16
	s_waitcnt lgkmcnt(3)
	v_pk_fma_f32 v[36:37], v[8:9], v[32:33], v[6:7]
	v_pk_fma_f32 v[110:111], v[8:9], v[56:57], v[6:7]
	v_pk_fma_f32 v[106:107], v[14:15], v[34:35], v[18:19]
	v_pk_fma_f32 v[112:113], v[14:15], v[58:59], v[18:19]
	v_pk_fma_f32 v[36:37], v[4:5], v[102:103], v[36:37]
	v_pk_fma_f32 v[110:111], v[4:5], v[32:33], v[110:111]
	v_pk_fma_f32 v[106:107], v[12:13], v[104:105], v[106:107]
	v_pk_fma_f32 v[112:113], v[12:13], v[34:35], v[112:113]
	v_pk_fma_f32 v[36:37], v[10:11], v[56:57], v[36:37]
	v_pk_fma_f32 v[110:111], v[10:11], v[60:61], v[110:111]
	v_pk_fma_f32 v[106:107], v[16:17], v[58:59], v[106:107]
	v_pk_fma_f32 v[112:113], v[16:17], v[62:63], v[112:113]
	v_mul_f32_e32 v31, 0xbfb8aa3b, v36
	v_mul_f32_e32 v116, 0xbfb8aa3b, v110
	v_exp_f32_e32 v31, v31
	v_exp_f32_e32 v116, v116
	v_add_f32_e32 v31, 1.0, v31
	v_add_f32_e32 v116, 1.0, v116
	v_rcp_f32_e32 v108, v31
	v_rcp_f32_e32 v114, v116
	v_mul_f32_e32 v31, 0xbfb8aa3b, v37
	v_mul_f32_e32 v116, 0xbfb8aa3b, v111
	v_exp_f32_e32 v31, v31
	v_exp_f32_e32 v116, v116
	v_add_f32_e32 v31, 1.0, v31
	v_add_f32_e32 v116, 1.0, v116
	v_rcp_f32_e32 v109, v31
	v_rcp_f32_e32 v115, v116
	v_pk_mul_f32 v[36:37], v[36:37], v[108:109]
	v_pk_mul_f32 v[110:111], v[110:111], v[114:115]
	v_pk_mul_f32 v[36:37], v[106:107], v[36:37]
	v_pk_mul_f32 v[110:111], v[112:113], v[110:111]
	v_cvt_pk_bf16_f32 v36, v36, v37
	v_cvt_pk_bf16_f32 v110, v110, v111
	global_store_dword v[20:21], v36, off
	v_lshl_add_u64 v[20:21], v[20:21], 0, s[38:39]
	global_store_dword v[20:21], v110, off
	v_lshl_add_u64 v[20:21], v[20:21], 0, s[38:39]
	ds_read2_b64 v[76:79], v117 offset0:64 offset1:80
	ds_read2_b64 v[102:105], v117 offset0:128 offset1:144
	s_waitcnt lgkmcnt(3)
	v_pk_fma_f32 v[36:37], v[8:9], v[60:61], v[6:7]
	v_pk_fma_f32 v[110:111], v[8:9], v[64:65], v[6:7]
	v_pk_fma_f32 v[106:107], v[14:15], v[62:63], v[18:19]
	v_pk_fma_f32 v[112:113], v[14:15], v[66:67], v[18:19]
	v_pk_fma_f32 v[36:37], v[4:5], v[56:57], v[36:37]
	v_pk_fma_f32 v[110:111], v[4:5], v[60:61], v[110:111]
	v_pk_fma_f32 v[106:107], v[12:13], v[58:59], v[106:107]
	v_pk_fma_f32 v[112:113], v[12:13], v[62:63], v[112:113]
	v_pk_fma_f32 v[36:37], v[10:11], v[64:65], v[36:37]
	v_pk_fma_f32 v[110:111], v[10:11], v[68:69], v[110:111]
	v_pk_fma_f32 v[106:107], v[16:17], v[66:67], v[106:107]
	v_pk_fma_f32 v[112:113], v[16:17], v[70:71], v[112:113]
	v_mul_f32_e32 v31, 0xbfb8aa3b, v36
	v_mul_f32_e32 v116, 0xbfb8aa3b, v110
	v_exp_f32_e32 v31, v31
	v_exp_f32_e32 v116, v116
	v_add_f32_e32 v31, 1.0, v31
	v_add_f32_e32 v116, 1.0, v116
	v_rcp_f32_e32 v108, v31
	v_rcp_f32_e32 v114, v116
	v_mul_f32_e32 v31, 0xbfb8aa3b, v37
	v_mul_f32_e32 v116, 0xbfb8aa3b, v111
	v_exp_f32_e32 v31, v31
	v_exp_f32_e32 v116, v116
	v_add_f32_e32 v31, 1.0, v31
	v_add_f32_e32 v116, 1.0, v116
	v_rcp_f32_e32 v109, v31
	v_rcp_f32_e32 v115, v116
	v_pk_mul_f32 v[36:37], v[36:37], v[108:109]
	v_pk_mul_f32 v[110:111], v[110:111], v[114:115]
	v_pk_mul_f32 v[36:37], v[106:107], v[36:37]
	v_pk_mul_f32 v[110:111], v[112:113], v[110:111]
	v_cvt_pk_bf16_f32 v36, v36, v37
	v_cvt_pk_bf16_f32 v110, v110, v111
	global_store_dword v[20:21], v36, off
	v_lshl_add_u64 v[20:21], v[20:21], 0, s[38:39]
	global_store_dword v[20:21], v110, off
	v_lshl_add_u64 v[20:21], v[20:21], 0, s[38:39]
	ds_read2_b64 v[32:35], v117 offset0:192 offset1:208
	s_waitcnt lgkmcnt(2)
	v_pk_fma_f32 v[36:37], v[8:9], v[68:69], v[6:7]
	v_pk_fma_f32 v[110:111], v[8:9], v[72:73], v[6:7]
	v_pk_fma_f32 v[106:107], v[14:15], v[70:71], v[18:19]
	v_pk_fma_f32 v[112:113], v[14:15], v[74:75], v[18:19]
	v_pk_fma_f32 v[36:37], v[4:5], v[64:65], v[36:37]
	v_pk_fma_f32 v[110:111], v[4:5], v[68:69], v[110:111]
	v_pk_fma_f32 v[106:107], v[12:13], v[66:67], v[106:107]
	v_pk_fma_f32 v[112:113], v[12:13], v[70:71], v[112:113]
	v_pk_fma_f32 v[36:37], v[10:11], v[72:73], v[36:37]
	v_pk_fma_f32 v[110:111], v[10:11], v[76:77], v[110:111]
	v_pk_fma_f32 v[106:107], v[16:17], v[74:75], v[106:107]
	v_pk_fma_f32 v[112:113], v[16:17], v[78:79], v[112:113]
	v_mul_f32_e32 v31, 0xbfb8aa3b, v36
	v_mul_f32_e32 v116, 0xbfb8aa3b, v110
	v_exp_f32_e32 v31, v31
	v_exp_f32_e32 v116, v116
	v_add_f32_e32 v31, 1.0, v31
	v_add_f32_e32 v116, 1.0, v116
	v_rcp_f32_e32 v108, v31
	v_rcp_f32_e32 v114, v116
	v_mul_f32_e32 v31, 0xbfb8aa3b, v37
	v_mul_f32_e32 v116, 0xbfb8aa3b, v111
	v_exp_f32_e32 v31, v31
	v_exp_f32_e32 v116, v116
	v_add_f32_e32 v31, 1.0, v31
	v_add_f32_e32 v116, 1.0, v116
	v_rcp_f32_e32 v109, v31
	v_rcp_f32_e32 v115, v116
	v_pk_mul_f32 v[36:37], v[36:37], v[108:109]
	v_pk_mul_f32 v[110:111], v[110:111], v[114:115]
	v_pk_mul_f32 v[36:37], v[106:107], v[36:37]
	v_pk_mul_f32 v[110:111], v[112:113], v[110:111]
	v_cvt_pk_bf16_f32 v36, v36, v37
	v_cvt_pk_bf16_f32 v110, v110, v111
	global_store_dword v[20:21], v36, off
	v_lshl_add_u64 v[20:21], v[20:21], 0, s[38:39]
	global_store_dword v[20:21], v110, off
	v_lshl_add_u64 v[20:21], v[20:21], 0, s[38:39]
	s_waitcnt lgkmcnt(0)
	v_pk_fma_f32 v[36:37], v[8:9], v[76:77], v[6:7]
	v_pk_fma_f32 v[110:111], v[8:9], v[102:103], v[6:7]
	v_pk_fma_f32 v[106:107], v[14:15], v[78:79], v[18:19]
	v_pk_fma_f32 v[112:113], v[14:15], v[104:105], v[18:19]
	v_pk_fma_f32 v[36:37], v[4:5], v[72:73], v[36:37]
	v_pk_fma_f32 v[110:111], v[4:5], v[76:77], v[110:111]
	v_pk_fma_f32 v[106:107], v[12:13], v[74:75], v[106:107]
	v_pk_fma_f32 v[112:113], v[12:13], v[78:79], v[112:113]
	v_pk_fma_f32 v[36:37], v[10:11], v[102:103], v[36:37]
	v_pk_fma_f32 v[110:111], v[10:11], v[32:33], v[110:111]
	v_pk_fma_f32 v[106:107], v[16:17], v[104:105], v[106:107]
	v_pk_fma_f32 v[112:113], v[16:17], v[34:35], v[112:113]
	v_mul_f32_e32 v31, 0xbfb8aa3b, v36
	v_mul_f32_e32 v116, 0xbfb8aa3b, v110
	v_exp_f32_e32 v31, v31
	v_exp_f32_e32 v116, v116
	v_add_f32_e32 v31, 1.0, v31
	v_add_f32_e32 v116, 1.0, v116
	v_rcp_f32_e32 v108, v31
	v_rcp_f32_e32 v114, v116
	v_mul_f32_e32 v31, 0xbfb8aa3b, v37
	v_mul_f32_e32 v116, 0xbfb8aa3b, v111
	v_exp_f32_e32 v31, v31
	v_exp_f32_e32 v116, v116
	v_add_f32_e32 v31, 1.0, v31
	v_add_f32_e32 v116, 1.0, v116
	v_rcp_f32_e32 v109, v31
	v_rcp_f32_e32 v115, v116
	v_pk_mul_f32 v[36:37], v[36:37], v[108:109]
	v_pk_mul_f32 v[110:111], v[110:111], v[114:115]
	v_pk_mul_f32 v[36:37], v[106:107], v[36:37]
	v_pk_mul_f32 v[110:111], v[112:113], v[110:111]
	v_cvt_pk_bf16_f32 v36, v36, v37
	v_cvt_pk_bf16_f32 v110, v110, v111
	global_store_dword v[20:21], v36, off
	v_lshl_add_u64 v[20:21], v[20:21], 0, s[38:39]
	s_and_saveexec_b64 s[2:3], vcc
	global_store_dword v[20:21], v110, off
	s_or_b64 exec, exec, s[2:3]
	s_branch .LBB0_1066
